# P0 weight-transpose loops (gain-optional paths): batch 8 row loads + 8 gain loads per wait instead of one load per vmcnt(0)
# speedup vs baseline: 1.0149x; 1.0149x over previous
.LBB0_55:
	v_cndmask_b32_e64 v4, 0, 1, s[20:21]
	s_nop 0
	v_cmp_ne_u32_e64 s[0:1], 1, v4
	v_mov_b32_e32 v144, 1.0
	v_mov_b32_e32 v146, 1.0
	v_mov_b32_e32 v148, 1.0
	v_mov_b32_e32 v150, 1.0
	v_mov_b32_e32 v152, 1.0
	v_mov_b32_e32 v154, 1.0
	v_mov_b32_e32 v156, 1.0
	v_mov_b32_e32 v158, 1.0
	s_and_b64 vcc, exec, s[20:21]
	s_cbranch_vccz .Lp0a_nogain
	v_lshl_add_u64 v[192:193], v[26:27], 0, v[30:31]
	global_load_dword v144, v[192:193], off
	v_lshl_add_u64 v[192:193], v[26:27], 0, v[30:31]
	global_load_dword v146, v[192:193], off offset:16
	global_load_dword v148, v[192:193], off offset:32
	global_load_dword v150, v[192:193], off offset:48
	global_load_dword v152, v[192:193], off offset:64
	global_load_dword v154, v[192:193], off offset:80
	global_load_dword v156, v[192:193], off offset:96
	global_load_dword v158, v[192:193], off offset:112
.Lp0a_nogain:
	v_lshl_add_u64 v[192:193], v[44:45], 0, s[44:45]
	global_load_dwordx4 v[160:163], v[192:193], off
	v_lshl_add_u64 v[192:193], v[42:43], 0, s[44:45]
	global_load_dwordx4 v[164:167], v[192:193], off
	v_lshl_add_u64 v[192:193], v[40:41], 0, s[44:45]
	global_load_dwordx4 v[168:171], v[192:193], off
	v_lshl_add_u64 v[192:193], v[38:39], 0, s[44:45]
	global_load_dwordx4 v[172:175], v[192:193], off
	v_lshl_add_u64 v[192:193], v[36:37], 0, s[44:45]
	global_load_dwordx4 v[176:179], v[192:193], off
	v_lshl_add_u64 v[192:193], v[34:35], 0, s[44:45]
	global_load_dwordx4 v[180:183], v[192:193], off
	v_lshl_add_u64 v[192:193], v[32:33], 0, s[44:45]
	global_load_dwordx4 v[184:187], v[192:193], off
	v_lshl_add_u64 v[192:193], v[28:29], 0, s[44:45]
	global_load_dwordx4 v[188:191], v[192:193], off
	s_add_u32 s44, s44, 0x60000
	s_addc_u32 s45, s45, 0
	v_lshl_add_u64 v[26:27], v[26:27], 0, s[30:31]
	s_waitcnt vmcnt(0)
	v_pk_mul_f32 v[160:161], v[144:145], v[160:161] op_sel_hi:[0,1]
	v_pk_mul_f32 v[162:163], v[144:145], v[162:163] op_sel_hi:[0,1]
	ds_write2_b32 v50, v160, v161 offset1:1
	ds_write2_b32 v50, v162, v163 offset0:2 offset1:3
	v_pk_mul_f32 v[164:165], v[146:147], v[164:165] op_sel_hi:[0,1]
	v_pk_mul_f32 v[166:167], v[146:147], v[166:167] op_sel_hi:[0,1]
	v_add_u32_e32 v194, 0x410, v50
	ds_write2_b32 v194, v164, v165 offset1:1
	ds_write2_b32 v194, v166, v167 offset0:2 offset1:3
	v_pk_mul_f32 v[168:169], v[148:149], v[168:169] op_sel_hi:[0,1]
	v_pk_mul_f32 v[170:171], v[148:149], v[170:171] op_sel_hi:[0,1]
	v_add_u32_e32 v194, 0x820, v50
	ds_write2_b32 v194, v168, v169 offset1:1
	ds_write2_b32 v194, v170, v171 offset0:2 offset1:3
	v_pk_mul_f32 v[172:173], v[150:151], v[172:173] op_sel_hi:[0,1]
	v_pk_mul_f32 v[174:175], v[150:151], v[174:175] op_sel_hi:[0,1]
	v_add_u32_e32 v194, 0xc30, v50
	ds_write2_b32 v194, v172, v173 offset1:1
	ds_write2_b32 v194, v174, v175 offset0:2 offset1:3
	v_pk_mul_f32 v[176:177], v[152:153], v[176:177] op_sel_hi:[0,1]
	v_pk_mul_f32 v[178:179], v[152:153], v[178:179] op_sel_hi:[0,1]
	v_add_u32_e32 v194, 0x1040, v50
	ds_write2_b32 v194, v176, v177 offset1:1
	ds_write2_b32 v194, v178, v179 offset0:2 offset1:3
	v_pk_mul_f32 v[180:181], v[154:155], v[180:181] op_sel_hi:[0,1]
	v_pk_mul_f32 v[182:183], v[154:155], v[182:183] op_sel_hi:[0,1]
	v_add_u32_e32 v194, 0x1450, v50
	ds_write2_b32 v194, v180, v181 offset1:1
	ds_write2_b32 v194, v182, v183 offset0:2 offset1:3
	v_pk_mul_f32 v[184:185], v[156:157], v[184:185] op_sel_hi:[0,1]
	v_pk_mul_f32 v[186:187], v[156:157], v[186:187] op_sel_hi:[0,1]
	v_add_u32_e32 v194, 0x1860, v50
	ds_write2_b32 v194, v184, v185 offset1:1
	ds_write2_b32 v194, v186, v187 offset0:2 offset1:3
	v_pk_mul_f32 v[188:189], v[158:159], v[188:189] op_sel_hi:[0,1]
	v_pk_mul_f32 v[190:191], v[158:159], v[190:191] op_sel_hi:[0,1]
	v_add_u32_e32 v194, 0x1c70, v50
	ds_write2_b32 v194, v188, v189 offset1:1
	ds_write2_b32 v194, v190, v191 offset0:2 offset1:3
	v_add_u32_e32 v50, 0x2080, v50
	s_cmp_lg_u32 s44, 0xc0000
	s_cbranch_scc1 .LBB0_55

.LBB0_82:
	v_cndmask_b32_e64 v4, 0, 1, s[26:27]
	s_nop 0
	v_cmp_ne_u32_e64 s[0:1], 1, v4
	v_mov_b32_e32 v144, 1.0
	v_mov_b32_e32 v146, 1.0
	v_mov_b32_e32 v148, 1.0
	v_mov_b32_e32 v150, 1.0
	v_mov_b32_e32 v152, 1.0
	v_mov_b32_e32 v154, 1.0
	v_mov_b32_e32 v156, 1.0
	v_mov_b32_e32 v158, 1.0
	s_and_b64 vcc, exec, s[26:27]
	s_cbranch_vccz .Lp0b_nogain
	v_lshl_add_u64 v[192:193], v[28:29], 0, v[32:33]
	global_load_dword v144, v[192:193], off
	v_lshl_add_u64 v[192:193], v[26:27], 0, v[32:33]
	global_load_dword v146, v[192:193], off offset:16
	global_load_dword v148, v[192:193], off offset:32
	global_load_dword v150, v[192:193], off offset:48
	global_load_dword v152, v[192:193], off offset:64
	global_load_dword v154, v[192:193], off offset:80
	global_load_dword v156, v[192:193], off offset:96
	global_load_dword v158, v[192:193], off offset:112
.Lp0b_nogain:
	v_lshl_add_u64 v[192:193], v[46:47], 0, s[42:43]
	global_load_dwordx4 v[160:163], v[192:193], off
	v_lshl_add_u64 v[192:193], v[44:45], 0, s[42:43]
	global_load_dwordx4 v[164:167], v[192:193], off
	v_lshl_add_u64 v[192:193], v[42:43], 0, s[42:43]
	global_load_dwordx4 v[168:171], v[192:193], off
	v_lshl_add_u64 v[192:193], v[40:41], 0, s[42:43]
	global_load_dwordx4 v[172:175], v[192:193], off
	v_lshl_add_u64 v[192:193], v[38:39], 0, s[42:43]
	global_load_dwordx4 v[176:179], v[192:193], off
	v_lshl_add_u64 v[192:193], v[36:37], 0, s[42:43]
	global_load_dwordx4 v[180:183], v[192:193], off
	v_lshl_add_u64 v[192:193], v[34:35], 0, s[42:43]
	global_load_dwordx4 v[184:187], v[192:193], off
	v_lshl_add_u64 v[192:193], v[30:31], 0, s[42:43]
	global_load_dwordx4 v[188:191], v[192:193], off
	s_add_u32 s42, s42, 0x80000
	s_addc_u32 s43, s43, 0
	v_lshl_add_u64 v[26:27], v[26:27], 0, s[30:31]
	v_lshl_add_u64 v[28:29], v[28:29], 0, s[30:31]
	s_waitcnt vmcnt(0)
	v_pk_mul_f32 v[160:161], v[144:145], v[160:161] op_sel_hi:[0,1]
	v_pk_mul_f32 v[162:163], v[144:145], v[162:163] op_sel_hi:[0,1]
	ds_write2_b32 v52, v160, v161 offset1:1
	ds_write2_b32 v52, v162, v163 offset0:2 offset1:3
	v_pk_mul_f32 v[164:165], v[146:147], v[164:165] op_sel_hi:[0,1]
	v_pk_mul_f32 v[166:167], v[146:147], v[166:167] op_sel_hi:[0,1]
	v_add_u32_e32 v194, 0x410, v52
	ds_write2_b32 v194, v164, v165 offset1:1
	ds_write2_b32 v194, v166, v167 offset0:2 offset1:3
	v_pk_mul_f32 v[168:169], v[148:149], v[168:169] op_sel_hi:[0,1]
	v_pk_mul_f32 v[170:171], v[148:149], v[170:171] op_sel_hi:[0,1]
	v_add_u32_e32 v194, 0x820, v52
	ds_write2_b32 v194, v168, v169 offset1:1
	ds_write2_b32 v194, v170, v171 offset0:2 offset1:3
	v_pk_mul_f32 v[172:173], v[150:151], v[172:173] op_sel_hi:[0,1]
	v_pk_mul_f32 v[174:175], v[150:151], v[174:175] op_sel_hi:[0,1]
	v_add_u32_e32 v194, 0xc30, v52
	ds_write2_b32 v194, v172, v173 offset1:1
	ds_write2_b32 v194, v174, v175 offset0:2 offset1:3
	v_pk_mul_f32 v[176:177], v[152:153], v[176:177] op_sel_hi:[0,1]
	v_pk_mul_f32 v[178:179], v[152:153], v[178:179] op_sel_hi:[0,1]
	v_add_u32_e32 v194, 0x1040, v52
	ds_write2_b32 v194, v176, v177 offset1:1
	ds_write2_b32 v194, v178, v179 offset0:2 offset1:3
	v_pk_mul_f32 v[180:181], v[154:155], v[180:181] op_sel_hi:[0,1]
	v_pk_mul_f32 v[182:183], v[154:155], v[182:183] op_sel_hi:[0,1]
	v_add_u32_e32 v194, 0x1450, v52
	ds_write2_b32 v194, v180, v181 offset1:1
	ds_write2_b32 v194, v182, v183 offset0:2 offset1:3
	v_pk_mul_f32 v[184:185], v[156:157], v[184:185] op_sel_hi:[0,1]
	v_pk_mul_f32 v[186:187], v[156:157], v[186:187] op_sel_hi:[0,1]
	v_add_u32_e32 v194, 0x1860, v52
	ds_write2_b32 v194, v184, v185 offset1:1
	ds_write2_b32 v194, v186, v187 offset0:2 offset1:3
	v_pk_mul_f32 v[188:189], v[158:159], v[188:189] op_sel_hi:[0,1]
	v_pk_mul_f32 v[190:191], v[158:159], v[190:191] op_sel_hi:[0,1]
	v_add_u32_e32 v194, 0x1c70, v52
	ds_write2_b32 v194, v188, v189 offset1:1
	ds_write2_b32 v194, v190, v191 offset0:2 offset1:3
	v_add_u32_e32 v52, 0x2080, v52
	s_cmp_lg_u32 s42, 0x100000
	s_cbranch_scc1 .LBB0_82
	s_branch .LBB0_33
